# grid barriers after Lat8 / wout / pool GEMM downgraded to per-XCD barriers (rows owned by one XCD group); on top of q-prep load hoist
# speedup vs baseline: 1.0056x; 1.0017x over previous
; #define GBAR() { bar_target += gridDim.x; grid_bar(ctl + 32, bar_target); }
; DI void grid_bar(unsigned* ctr, unsigned target) {
;   asm volatile("s_waitcnt vmcnt(0)" ::: "memory");
;   __syncthreads();
;   if (threadIdx.x == 0) {
;     __builtin_amdgcn_fence(__ATOMIC_RELEASE, "agent");
;     asm volatile("s_waitcnt vmcnt(0)" ::: "memory");
;     (void)__hip_atomic_fetch_add(ctr, 1u, __ATOMIC_RELAXED, __HIP_MEMORY_SCOPE_AGENT);
;     while (__hip_atomic_load(ctr, __ATOMIC_RELAXED, __HIP_MEMORY_SCOPE_AGENT) < target) __builtin_amdgcn_s_sleep(1);
;     __builtin_amdgcn_fence(__ATOMIC_ACQUIRE, "agent");
;     asm volatile("s_waitcnt vmcnt(0)" ::: "memory");
;   }
;   __syncthreads();
; }
; __global__ void __launch_bounds__(512, 2) fwd_megakernel(Params p) {
;     ...
;       gemm8_phase(xs, js, hb, LDH, win + (size_t)jl * LATNP * (D + PADK), D, LATNP, 0, EpiLat8{lat, kpe, ssq_q, ssq_kv, ssq1});
;       GBAR();
.LBB0_1240:
	s_waitcnt vmcnt(0)
	v_readlane_b32 s0, v254, 12
	v_readlane_b32 s1, v253, 38
	s_mov_b32 s6, s1
	v_readlane_b32 s32, v253, 35
	v_readlane_b32 s14, v254, 52
	v_readlane_b32 s15, v254, 53
	s_add_i32 s32, s32, s33
	s_waitcnt lgkmcnt(0)
	s_barrier
	s_mov_b64 s[0:1], exec
	v_readlane_b32 s2, v254, 13
	v_readlane_b32 s3, v254, 14
	s_and_b64 s[2:3], s[0:1], s[2:3]
	s_movk_i32 s79, 0xffe0
	s_mov_b64 exec, s[2:3]
	s_cbranch_execz .LBB0_1246
	s_mov_b64 s[2:3], exec
	buffer_wbl2 sc1
	s_waitcnt vmcnt(0)
	s_waitcnt vmcnt(0)
	v_mbcnt_lo_u32_b32 v0, s2, 0
	v_mbcnt_hi_u32_b32 v0, s3, v0
	v_cmp_eq_u32_e32 vcc, 0, v0
	s_and_saveexec_b64 s[8:9], vcc
	s_cbranch_execz .LBB0_1243
	s_bcnt1_i32_b64 s2, s[2:3]
	v_mov_b32_e32 v0, s2
	global_atomic_add v1, v0, s[14:15]
.LBB0_1243:
	s_or_b64 exec, exec, s[8:9]
	global_load_dword v0, v1, s[14:15] sc1
	s_waitcnt vmcnt(0)
	v_cmp_le_u32_e32 vcc, s32, v0
	s_cbranch_vccnz .LBB0_1245
.LBB0_1244:
	s_sleep 1
	global_load_dword v0, v1, s[14:15] sc1
	s_waitcnt vmcnt(0)
	v_cmp_gt_u32_e32 vcc, s32, v0
	s_cbranch_vccnz .LBB0_1244

; #define GBAR() { bar_target += gridDim.x; grid_bar(ctl + 32, bar_target); }
; __global__ void __launch_bounds__(512, 2) fwd_megakernel(Params p) {
;     ...
;       GBAR();
;       gemm8_phase(xs, js, lat, LDH, wq + (size_t)jl * 1536 * (QL + PADK), QL, 1536, 0, EpiQraw8{qraw, ssq_q});
.LBB0_1246:
	s_or_b64 exec, exec, s[0:1]
	v_writelane_b32 v253, s32, 35
	v_readlane_b32 s14, v253, 29
	v_readlane_b32 s15, v253, 30
	v_readlane_b32 s0, v254, 59
	v_readlane_b32 s1, v254, 60
	s_andn2_b64 vcc, exec, s[0:1]
	s_barrier
	v_writelane_b32 v253, s5, 41
	s_cbranch_vccnz .LBB0_1260
	s_mul_hi_u32 s0, s5, 0x270000
	s_mul_i32 s1, s5, 0x270000
	v_readlane_b32 s2, v254, 36
	v_readlane_b32 s4, v253, 39
	s_add_u32 s2, s2, s1
	v_readlane_b32 s1, v254, 37
	v_readlane_b32 s5, v253, 40
	s_addc_u32 s3, s1, s0
	s_mul_i32 s0, s5, 0x270000
	s_mul_hi_u32 s1, s4, 0x270000
	s_add_i32 s1, s1, s0
	s_mul_i32 s0, s4, 0x270000
	v_readlane_b32 s4, v253, 12
	s_add_u32 s57, s4, s0
	v_readlane_b32 s0, v253, 13
	s_addc_u32 s58, s0, s1
	s_mov_b64 s[0:1], 0
	v_readlane_b32 s59, v254, 58
	s_branch .LBB0_1249

; DI void grid_bar(unsigned* ctr, unsigned target) {
;   asm volatile("s_waitcnt vmcnt(0)" ::: "memory");
;   __syncthreads();
;   if (threadIdx.x == 0) {
;     __builtin_amdgcn_fence(__ATOMIC_RELEASE, "agent");
;     asm volatile("s_waitcnt vmcnt(0)" ::: "memory");
;     (void)__hip_atomic_fetch_add(ctr, 1u, __ATOMIC_RELAXED, __HIP_MEMORY_SCOPE_AGENT);
;     while (__hip_atomic_load(ctr, __ATOMIC_RELAXED, __HIP_MEMORY_SCOPE_AGENT) < target) __builtin_amdgcn_s_sleep(1);
;     __builtin_amdgcn_fence(__ATOMIC_ACQUIRE, "agent");
.LBB0_1460:
	s_waitcnt vmcnt(0)
	v_readlane_b32 s0, v254, 12
	s_mov_b32 s74, s56
	v_readlane_b32 s32, v253, 35
	v_readlane_b32 s14, v254, 52
	v_readlane_b32 s15, v254, 53
	s_add_i32 s32, s32, s33
	s_barrier
	s_mov_b64 s[0:1], exec
	v_readlane_b32 s2, v254, 13
	v_readlane_b32 s3, v254, 14
	s_and_b64 s[2:3], s[0:1], s[2:3]
	s_mov_b64 exec, s[2:3]
	s_cbranch_execz .LBB0_1466
	s_mov_b64 s[2:3], exec
	buffer_wbl2 sc1
	s_waitcnt vmcnt(0)
	s_waitcnt vmcnt(0)
	v_mbcnt_lo_u32_b32 v0, s2, 0
	v_mbcnt_hi_u32_b32 v0, s3, v0
	v_cmp_eq_u32_e32 vcc, 0, v0
	s_and_saveexec_b64 s[8:9], vcc
	s_cbranch_execz .LBB0_1463
	s_bcnt1_i32_b64 s2, s[2:3]
	v_mov_b32_e32 v0, s2
	global_atomic_add v1, v0, s[14:15]

; DI void grid_bar(unsigned* ctr, unsigned target) {
;     ...
;   }
;   __syncthreads();
; }
.LBB0_1466:
	s_or_b64 exec, exec, s[0:1]
	v_writelane_b32 v253, s32, 35
	v_readlane_b32 s14, v253, 29
	v_readlane_b32 s15, v253, 30
	s_barrier
	s_mov_b64 s[0:1], 0

; DI void grid_bar(unsigned* ctr, unsigned target) {
;   asm volatile("s_waitcnt vmcnt(0)" ::: "memory");
;   __syncthreads();
;   if (threadIdx.x == 0) {
;     __builtin_amdgcn_fence(__ATOMIC_RELEASE, "agent");
;     asm volatile("s_waitcnt vmcnt(0)" ::: "memory");
;     (void)__hip_atomic_fetch_add(ctr, 1u, __ATOMIC_RELAXED, __HIP_MEMORY_SCOPE_AGENT);
;     while (__hip_atomic_load(ctr, __ATOMIC_RELAXED, __HIP_MEMORY_SCOPE_AGENT) < target) __builtin_amdgcn_s_sleep(1);
;     __builtin_amdgcn_fence(__ATOMIC_ACQUIRE, "agent");
;     asm volatile("s_waitcnt vmcnt(0)" ::: "memory");
;   }
;   __syncthreads();
; }
.LBB0_1658:
	s_waitcnt vmcnt(0)
	v_readlane_b32 s0, v254, 12
	s_mov_b32 s74, s58
	v_readlane_b32 s32, v253, 35
	v_readlane_b32 s14, v254, 52
	v_readlane_b32 s15, v254, 53
	s_add_i32 s32, s32, s33
	s_barrier
	s_mov_b64 s[0:1], exec
	v_readlane_b32 s2, v254, 13
	v_readlane_b32 s3, v254, 14
	s_and_b64 s[2:3], s[0:1], s[2:3]
	s_mov_b64 exec, s[2:3]
	s_cbranch_execz .LBB0_1664
	s_mov_b64 s[2:3], exec
	buffer_wbl2 sc1
	s_waitcnt vmcnt(0)
	s_waitcnt vmcnt(0)
	v_mbcnt_lo_u32_b32 v0, s2, 0
	v_mbcnt_hi_u32_b32 v0, s3, v0
	v_cmp_eq_u32_e32 vcc, 0, v0
	s_and_saveexec_b64 s[6:7], vcc
	s_cbranch_execz .LBB0_1661
	s_bcnt1_i32_b64 s2, s[2:3]
	v_mov_b32_e32 v0, s2
	global_atomic_add v1, v0, s[14:15]
.LBB0_1661:
	s_or_b64 exec, exec, s[6:7]
	global_load_dword v0, v1, s[14:15] sc1
	s_waitcnt vmcnt(0)
	v_cmp_le_u32_e32 vcc, s32, v0
	s_cbranch_vccnz .LBB0_1663

; DI void grid_bar(unsigned* ctr, unsigned target) {
;     ...
;   }
;   __syncthreads();
; }
.LBB0_1664:
	s_or_b64 exec, exec, s[0:1]
	v_writelane_b32 v253, s32, 35
	v_readlane_b32 s14, v253, 29
	v_readlane_b32 s15, v253, 30
	s_barrier
